# v9 + one static s_setprio 1 for waves 4-7 (younger wave per SIMD) across the attention phase, reset to 0 at phase exit
# speedup vs baseline: 1.0013x; 1.0013x over previous
; #define LAS __attribute__((address_space(3)))
; DI void attn_phase(LAS unsigned char* lds, ArgsRef a, int l, int vcu, int G) {
;     ...
;     const int NLAT = 8192, nitems = NLAT + (l == 0 ? 1024 : 0);
;     const float SC = 0.125f * LOG2E;
;     const int pil = (li & 0x13) | ((li & 4) << 1) | ((li & 8) >> 1);
;     constexpr int KL_OFF = 32768, KL_PITCH = 144, VL_OFF = KL_OFF + 256 * KL_PITCH, VL_PITCH = 528;
;     static_assert(VL_OFF + 64 * VL_PITCH <= 131072, "attention LDS map");
;     for (int bi = vcu; bi * 8 < nitems; bi += G) {
;         const int item = bi * 8 + wid;
;         const bool isctx = item >= NLAT;
;         int b, h, row = 0, gq0;
;         if (!isctx) { row = item & 63; h = (item >> 6) & 15; b = item >> 10; gq0 = b * TL + row * 64 + li; }
;         else { const int it = item - NLAT, qb = it & 7; h = (it >> 3) & 15; b = it >> 7; gq0 = MLAT + b * TCX + qb * 32 + li; }
;         __syncthreads();
;         {
;             const char* ksrc = (const char*)(KH + ((size_t)h * MALL + MLAT + b * TCX) * 64);
;             const char* vsrc = (const char*)(VT + (size_t)(h * 64) * MALL + MLAT + b * TCX);
;             u32x4 kv[4], vv[4];
; #pragma unroll
;             for (int i = 0; i < 4; ++i) { const int q = tid + 512 * i; kv[i] = *(const u32x4*)(ksrc + (size_t)q * 16); vv[i] = *(const u32x4*)(vsrc + (size_t)(q >> 5) * MALL * 2 + (q & 31) * 16); }
; #pragma unroll
;             for (int i = 0; i < 4; ++i) { const int q = tid + 512 * i;
;                 *(LAS u32x4*)(lds + KL_OFF + (q >> 3) * KL_PITCH + (q & 7) * 16) = kv[i];
;                 *(LAS u32x4*)(lds + VL_OFF + (q >> 5) * VL_PITCH + (q & 31) * 16) = vv[i]; }
;         }
;         __syncthreads();
;         const int rs = row - 4 < 0 ? 0 : (row - 4 > 56 ? 56 : row - 4);
;         bf16x8 qfA[4], qfB[4];
;         { const bf16x8* qp = (const bf16x8*)(QH + ((size_t)h * MALL + gq0) * 64 + hg * 32);
; #pragma unroll
;           for (int c = 0; c < 4; ++c) { qfA[c] = qp[c]; qfB[c] = isctx ? qp[c] : qp[c + 32 * 8]; } }
;         f32x16 oA0, oA1, oB0, oB1;
; #pragma unroll
;         for (int i = 0; i < 16; ++i) { oA0[i] = 0.f; oA1[i] = 0.f; oB0[i] = 0.f; oB1[i] = 0.f; }
;         float mA = -1e30f, lA = 0.f, mB = -1e30f, lB = 0.f;
;         const int ntiles = isctx ? 8 : 24;
.LBB0_337:
	s_or_b64 exec, exec, s[0:1]
	v_readlane_b32 s0, v254, 36
	v_readlane_b32 s1, v254, 37
	s_and_b64 s[0:1], s[0:1], exec
	s_movk_i32 s0, 0x2400
	s_cselect_b32 s14, s0, 0x2000
	v_readlane_b32 s0, v253, 13
	s_cmp_ge_i32 s0, s14
	s_waitcnt lgkmcnt(0)
	s_barrier
	s_cbranch_scc1 .LBB0_443
	v_lshlrev_b32_e32 v2, 4, v0
	v_and_b32_e32 v164, 0x1f0, v2
	v_and_b32_e32 v2, 0x70, v2
	v_lshlrev_b32_e32 v1, 1, v0
	v_add_u32_e32 v14, 0, v2
	v_xor_b32_e32 v2, 32, v231
	v_and_b32_e32 v12, 8, v1
	v_lshrrev_b32_e32 v1, 1, v0
	s_ashr_i32 s15, s20, 6
	v_cmp_lt_i32_e32 vcc, v2, v232
	v_and_b32_e32 v13, 4, v1
	v_bfe_u32 v1, v0, 5, 1
	s_lshl_b32 s0, s15, 5
	v_cndmask_b32_e32 v2, v231, v2, vcc
	v_and_b32_e32 v205, 31, v0
	s_and_b32 s20, s0, 0xe0
	s_add_i32 s0, 0, 0x11000
	v_lshlrev_b32_e32 v216, 2, v2
	v_lshlrev_b32_e32 v2, 4, v1
	v_mov_b32_e32 v3, v185
	v_add_u32_e32 v6, 0x200, v0
	v_add_u32_e32 v8, 0x400, v0
	v_add_u32_e32 v15, s0, v164
	v_lshlrev_b32_e32 v184, 6, v1
	v_readlane_b32 s0, v254, 39
	v_lshlrev_b32_e32 v217, 3, v1
	v_lshl_add_u64 v[170:171], s[18:19], 0, v[2:3]
	v_min_u32_e32 v3, 24, v205
	v_lshlrev_b32_e32 v4, 2, v1
	v_ashrrev_i32_e32 v1, 31, v0
	v_ashrrev_i32_e32 v7, 31, v6
	v_ashrrev_i32_e32 v9, 31, v8
	v_add_u32_e32 v10, 0x600, v0
	v_readlane_b32 s1, v254, 40
	v_add_u32_e32 v219, 24, v3
	v_add_u32_e32 v220, 40, v3
	v_lshlrev_b64 v[172:173], 4, v[0:1]
	v_ashrrev_i32_e32 v1, 5, v0
	s_mov_b32 s6, 0x11000
	v_lshlrev_b64 v[176:177], 4, v[6:7]
	v_ashrrev_i32_e32 v3, 5, v6
	v_lshlrev_b64 v[180:181], 4, v[8:9]
	v_ashrrev_i32_e32 v7, 5, v8
	v_ashrrev_i32_e32 v9, 5, v10
	v_and_b32_e32 v5, 19, v0
	v_lshl_add_u64 v[166:167], s[0:1], 0, v[184:185]
	v_mad_i64_i32 v[174:175], s[0:1], v1, s6, 0
	v_mad_i64_i32 v[178:179], s[0:1], v3, s6, 0
	v_mad_i64_i32 v[182:183], s[0:1], v7, s6, 0
	v_ashrrev_i32_e32 v11, 31, v10
	v_mad_i64_i32 v[196:197], s[0:1], v9, s6, 0
	v_or3_b32 v214, v13, v5, v12
	v_lshlrev_b64 v[194:195], 4, v[10:11]
	v_lshrrev_b32_e32 v0, 3, v0
	s_movk_i32 s0, 0x90
	s_movk_i32 s1, 0x210
	v_lshrrev_b32_e32 v6, 3, v6
	v_lshrrev_b32_e32 v8, 3, v8
	v_lshrrev_b32_e32 v10, 3, v10
	v_or3_b32 v5, v5, v12, v13
	v_sub_u32_e64 v215, v205, 8 clamp
	v_mul_lo_u32 v0, v0, s0
	v_mul_lo_u32 v1, v1, s1
	v_mul_lo_u32 v6, v6, s0
	v_mul_lo_u32 v3, v3, s1
	v_mul_lo_u32 v8, v8, s0
	v_mul_lo_u32 v7, v7, s1
	v_mul_lo_u32 v10, v10, s0
	v_mul_lo_u32 v9, v9, s1
	v_mad_u32_u24 v5, v5, s0, v184
	s_bitset1_b32 s20, 15
	v_mov_b32_e32 v165, v185
	v_lshl_add_u64 v[168:169], s[16:17], 0, v[184:185]
	v_add_u32_e32 v218, 16, v215
	v_or_b32_e32 v221, 0x8000, v5
	v_mad_u32_u24 v222, v205, s1, v2
	v_add_u32_e32 v223, v14, v0
	v_add_u32_e32 v224, v15, v1
	v_add_u32_e32 v225, v14, v6
	v_add_u32_e32 v226, v15, v3
	v_add_u32_e32 v242, v14, v8
	v_add_u32_e32 v243, v15, v7
	v_add_u32_e32 v244, v14, v10
	v_add_u32_e32 v245, v15, v9
	v_lshlrev_b32_e32 v198, 1, v4
	v_readlane_b32 s0, v253, 13
	s_mov_b32 s21, s94
	v_readfirstlane_b32 s6, v187
	s_cmpk_lt_u32 s6, 0x100
	s_cbranch_scc1 .Lattn_prio_skip
	s_setprio 1
.Lattn_prio_skip:
	s_branch .LBB0_340
.LBB0_339:
	s_add_i32 s21, s21, s3
	s_lshl_b32 s0, s21, 3
	s_cmp_ge_i32 s0, s14
	s_cbranch_scc1 .LBB0_443

; DI void attn_phase(LAS unsigned char* lds, ArgsRef a, int l, int vcu, int G) {
;     ...
;     for (int bi = vcu; bi * 8 < nitems; bi += G) {
;     ...
;     }
; }
.LBB0_443:
	s_setprio 0
	s_mov_b64 s[0:1], 0
